# FFN up/gate epilogue: dead zero-init v_mov removed + SS3 row-sum loads of rows +48/+0xb0 hoisted into the previous load batch (2 fewer exposed L2 round trips per tile)
# speedup vs baseline: 1.0086x; 1.0086x over previous
; #define LAS __attribute__((address_space(3)))
; #define FOR_AI_M _Pragma("unroll") for (int ai = 0; ai < 2; ++ai) _Pragma("unroll") for (int m = 0; m < 4; ++m)
; #define FOR_BJ _Pragma("unroll") for (int bj = 0; bj < 2; ++bj)
;     __device__ __forceinline__ void operator()(f32x4 (&acc)[2][2][4][2], const Unit& u, int wr, int wc, int fr, int fq) const {
;     ...
;         FOR_AI_M { const int grow = u.pm * BM + ai * HALF + wr * 64 + m * 16 + fr;
;             const f32x4 a0 = *(const f32x4*)(SS3 + (size_t)grow * 8), a1 = *(const f32x4*)(SS3 + (size_t)grow * 8 + 4);
;             const float r3 = rsqrtf(((a0[0] + a0[1]) + (a0[2] + a0[3]) + (a1[0] + a1[1]) + (a1[2] + a1[3])) * (1.f / 2048.f) + EPS);
;             FOR_BJ { acc[ai][bj][m][0] *= r3; acc[ai][bj][m][1] *= r3; } }
;         if (fr >= 14) {
; #pragma unroll
;             for (int ai = 0; ai < 2; ++ai) { LAS float* xp = XH + ((2 * ai + wr) * 2 + (fr - 14)) * 128 + 32 * wc + 8 * fq; *(LAS f32x4*)xp = acc[ai][0][3][0]; *(LAS f32x4*)(xp + 4) = acc[ai][0][3][1]; } }
.LBB0_1157:
	s_lshl_b32 s61, s70, 8
	s_add_i32 s63, s61, s79
	v_or_b32_e32 v220, s63, v190
	v_ashrrev_i32_e32 v221, 31, v220
	v_lshlrev_b64 v[72:73], 5, v[220:221]
	v_or_b32_e32 v216, 16, v220
	s_waitcnt vmcnt(0)
	v_lshl_add_u64 v[72:73], s[86:87], 0, v[72:73]
	v_ashrrev_i32_e32 v217, 31, v216
	global_load_dwordx4 v[152:155], v[72:73], off offset:16
	global_load_dwordx4 v[156:159], v[72:73], off
	v_lshlrev_b64 v[72:73], 5, v[216:217]
	v_or_b32_e32 v212, 32, v220
	v_lshl_add_u64 v[72:73], s[86:87], 0, v[72:73]
	v_ashrrev_i32_e32 v213, 31, v212
	global_load_dwordx4 v[104:107], v[72:73], off offset:16
	global_load_dwordx4 v[108:111], v[72:73], off
	v_lshlrev_b64 v[72:73], 5, v[212:213]
	v_lshl_add_u64 v[76:77], s[86:87], 0, v[72:73]
	global_load_dwordx4 v[72:75], v[76:77], off offset:16
	s_nop 0
	global_load_dwordx4 v[76:79], v[76:77], off
	v_or_b32_e32 v210, 48, v220
	v_ashrrev_i32_e32 v211, 31, v210
	v_lshlrev_b64 v[252:253], 5, v[210:211]
	v_lshl_add_u64 v[252:253], s[86:87], 0, v[252:253]
	global_load_dwordx4 v[244:247], v[252:253], off offset:16
	global_load_dwordx4 v[248:251], v[252:253], off
	s_mov_b32 s8, 0x358637bd
	v_mov_b64_e32 v[164:165], s[8:9]
	v_add_u32_e32 v208, 0x80, v220
	v_ashrrev_i32_e32 v209, 31, v208
	v_add_u32_e32 v204, 0x90, v220
	v_add_u32_e32 v206, 0xa0, v220
	v_ashrrev_i32_e32 v205, 31, v204
	v_ashrrev_i32_e32 v207, 31, v206
	v_lshlrev_b64 v[160:161], 5, v[206:207]
	v_lshl_add_u64 v[166:167], s[86:87], 0, v[160:161]
	v_add_u32_e32 v202, 0xb0, v220
	v_ashrrev_i32_e32 v203, 31, v202
	s_waitcnt vmcnt(0)
	v_mov_b32_e32 v80, v77
	v_mov_b32_e32 v81, v78
	v_mov_b32_e32 v77, v79
	v_pk_add_f32 v[80:81], v[80:81], v[76:77]
	v_mov_b32_e32 v76, v74
	v_mov_b32_e32 v77, v72
	v_mov_b32_e32 v72, v75
	v_pk_add_f32 v[82:83], v[76:77], v[72:73]
	v_mov_b64_e32 v[72:73], v[244:245]
	v_mov_b64_e32 v[74:75], v[246:247]
	v_mov_b64_e32 v[76:77], v[248:249]
	v_mov_b64_e32 v[78:79], v[250:251]
	v_mov_b32_e32 v84, v77
	v_mov_b32_e32 v85, v78
	v_mov_b32_e32 v77, v79
	v_pk_add_f32 v[76:77], v[84:85], v[76:77]
	v_mov_b32_e32 v78, v74
	v_mov_b32_e32 v79, v72
	v_mov_b32_e32 v72, v75
	v_pk_add_f32 v[72:73], v[78:79], v[72:73]
	v_mov_b32_e32 v74, v76
	v_mov_b32_e32 v75, v80
	v_mov_b32_e32 v80, v77
	v_pk_add_f32 v[74:75], v[74:75], v[80:81]
	v_mov_b32_e32 v76, v73
	v_mov_b32_e32 v77, v83
	v_pk_add_f32 v[74:75], v[74:75], v[76:77]
	v_mov_b32_e32 v73, v82
	v_pk_add_f32 v[72:73], v[72:73], v[74:75]
	s_nop 0
	v_pk_fma_f32 v[214:215], v[72:73], s[58:59], v[164:165] op_sel_hi:[1,0,0]
	s_nop 0
	v_cmp_gt_f32_e32 vcc, s85, v214
	v_mul_f32_e32 v72, 0x4b800000, v214
	v_cmp_gt_f32_e64 s[12:13], s85, v215
	v_cndmask_b32_e32 v72, v214, v72, vcc
	v_rsq_f32_e32 v72, v72
	s_nop 0
	v_mul_f32_e32 v73, 0x45800000, v72
	v_cndmask_b32_e32 v224, v72, v73, vcc
	v_pk_mul_f32 v[80:81], v[64:65], v[224:225] op_sel_hi:[1,0]
	v_lshlrev_b64 v[64:65], 5, v[208:209]
	v_lshl_add_u64 v[64:65], s[86:87], 0, v[64:65]
	global_load_dwordx4 v[72:75], v[64:65], off offset:16
	global_load_dwordx4 v[76:79], v[64:65], off
	v_lshlrev_b64 v[64:65], 5, v[204:205]
	v_pk_mul_f32 v[84:85], v[68:69], v[224:225] op_sel_hi:[1,0]
	v_lshl_add_u64 v[68:69], s[86:87], 0, v[64:65]
	v_pk_mul_f32 v[86:87], v[70:71], v[224:225] op_sel_hi:[1,0]
	v_pk_mul_f32 v[82:83], v[66:67], v[224:225] op_sel_hi:[1,0]
	global_load_dwordx4 v[64:67], v[68:69], off offset:16
	s_nop 0
	global_load_dwordx4 v[68:71], v[68:69], off
	s_nop 0
	global_load_dwordx4 v[160:163], v[166:167], off offset:16
	s_nop 0
	global_load_dwordx4 v[166:169], v[166:167], off
	v_lshlrev_b64 v[252:253], 5, v[202:203]
	v_lshl_add_u64 v[252:253], s[86:87], 0, v[252:253]
	global_load_dwordx4 v[244:247], v[252:253], off offset:16
	global_load_dwordx4 v[248:251], v[252:253], off
	s_waitcnt vmcnt(0)
	v_mov_b32_e32 v170, v167
	v_mov_b32_e32 v171, v168
	v_mov_b32_e32 v167, v169
	v_pk_add_f32 v[168:169], v[170:171], v[166:167]
	v_mov_b32_e32 v166, v162
	v_mov_b32_e32 v167, v160
	v_mov_b32_e32 v160, v163
	v_pk_add_f32 v[166:167], v[166:167], v[160:161]
	v_mov_b64_e32 v[160:161], v[244:245]
	v_mov_b64_e32 v[162:163], v[246:247]
	v_mov_b64_e32 v[170:171], v[248:249]
	v_mov_b64_e32 v[172:173], v[250:251]
	v_mov_b32_e32 v174, v171
	v_mov_b32_e32 v175, v172
	v_mov_b32_e32 v171, v173
	v_pk_add_f32 v[170:171], v[174:175], v[170:171]
	v_mov_b32_e32 v172, v162
	v_mov_b32_e32 v173, v160
	v_mov_b32_e32 v160, v163
	v_pk_add_f32 v[160:161], v[172:173], v[160:161]
	v_mov_b32_e32 v162, v170
	v_mov_b32_e32 v163, v168
	v_mov_b32_e32 v168, v171
	v_pk_add_f32 v[162:163], v[162:163], v[168:169]
	v_mov_b32_e32 v168, v161
	v_mov_b32_e32 v169, v167
	v_pk_add_f32 v[162:163], v[162:163], v[168:169]
	v_mov_b32_e32 v161, v166
	v_pk_add_f32 v[160:161], v[160:161], v[162:163]
	s_nop 0
	v_pk_fma_f32 v[218:219], v[160:161], s[58:59], v[164:165] op_sel_hi:[1,0,0]
	s_nop 0
	v_cmp_gt_f32_e32 vcc, s85, v218
	v_mul_f32_e32 v160, 0x4b800000, v218
	v_cmp_gt_f32_e64 s[8:9], s85, v219
	v_cndmask_b32_e32 v160, v218, v160, vcc
	v_rsq_f32_e32 v160, v160
	s_nop 0
	v_mul_f32_e32 v161, 0x45800000, v160
	v_cndmask_b32_e32 v214, v160, v161, vcc
	v_pk_mul_f32 v[62:63], v[62:63], v[214:215] op_sel_hi:[1,0]
	v_pk_mul_f32 v[60:61], v[60:61], v[214:215] op_sel_hi:[1,0]
	v_pk_mul_f32 v[58:59], v[58:59], v[214:215] op_sel_hi:[1,0]
	v_pk_mul_f32 v[56:57], v[56:57], v[214:215] op_sel_hi:[1,0]
	s_and_saveexec_b64 s[10:11], s[48:49]
	s_cbranch_execz .LBB0_1159
	ds_write_b128 v195, v[84:87]
	ds_write_b128 v195, v[80:83] offset:16
	ds_write_b128 v191, v[60:63]
	ds_write_b128 v191, v[56:59] offset:16

; __global__ void __launch_bounds__(512, 2) fwd_kernel(Args a) {
	.amdhsa_kernel _Z10fwd_kernel4Args
		.amdhsa_group_segment_fixed_size 0
		.amdhsa_private_segment_fixed_size 0
		.amdhsa_kernarg_size 528
		.amdhsa_user_sgpr_count 2
		.amdhsa_user_sgpr_dispatch_ptr 0
		.amdhsa_user_sgpr_queue_ptr 0
		.amdhsa_user_sgpr_kernarg_segment_ptr 1
		.amdhsa_user_sgpr_dispatch_id 0
		.amdhsa_user_sgpr_kernarg_preload_length 0
		.amdhsa_user_sgpr_kernarg_preload_offset 0
		.amdhsa_user_sgpr_private_segment_size 0
		.amdhsa_uses_dynamic_stack 0
		.amdhsa_enable_private_segment 0
		.amdhsa_system_sgpr_workgroup_id_x 1
		.amdhsa_system_sgpr_workgroup_id_y 0
		.amdhsa_system_sgpr_workgroup_id_z 0
		.amdhsa_system_sgpr_workgroup_info 0
		.amdhsa_system_vgpr_workitem_id 2
		.amdhsa_next_free_vgpr 256
		.amdhsa_next_free_sgpr 98
		.amdhsa_accum_offset 256
		.amdhsa_reserve_vcc 1
		.amdhsa_float_round_mode_32 0
		.amdhsa_float_round_mode_16_64 0
		.amdhsa_float_denorm_mode_32 3
		.amdhsa_float_denorm_mode_16_64 3
		.amdhsa_dx10_clamp 1
		.amdhsa_ieee_mode 1
		.amdhsa_fp16_overflow 0
		.amdhsa_tg_split 0
		.amdhsa_exception_fp_ieee_invalid_op 0
		.amdhsa_exception_fp_denorm_src 0
		.amdhsa_exception_fp_ieee_div_zero 0
		.amdhsa_exception_fp_ieee_overflow 0
		.amdhsa_exception_fp_ieee_underflow 0
		.amdhsa_exception_fp_ieee_inexact 0
		.amdhsa_exception_int_div_zero 0
	.end_amdhsa_kernel

; __global__ void __launch_bounds__(512, 2) fwd_kernel(Args a) {
amdhsa.kernels:
  - .agpr_count:     0
    .args:
      - .offset:         0
        .size:           272
        .value_kind:     by_value
      - .offset:         272
        .size:           4
        .value_kind:     hidden_block_count_x
      - .offset:         276
        .size:           4
        .value_kind:     hidden_block_count_y
      - .offset:         280
        .size:           4
        .value_kind:     hidden_block_count_z
      - .offset:         284
        .size:           2
        .value_kind:     hidden_group_size_x
      - .offset:         286
        .size:           2
        .value_kind:     hidden_group_size_y
      - .offset:         288
        .size:           2
        .value_kind:     hidden_group_size_z
      - .offset:         290
        .size:           2
        .value_kind:     hidden_remainder_x
      - .offset:         292
        .size:           2
        .value_kind:     hidden_remainder_y
      - .offset:         294
        .size:           2
        .value_kind:     hidden_remainder_z
      - .offset:         312
        .size:           8
        .value_kind:     hidden_global_offset_x
      - .offset:         320
        .size:           8
        .value_kind:     hidden_global_offset_y
      - .offset:         328
        .size:           8
        .value_kind:     hidden_global_offset_z
      - .offset:         336
        .size:           2
        .value_kind:     hidden_grid_dims
      - .offset:         360
        .size:           8
        .value_kind:     hidden_multigrid_sync_arg
      - .offset:         392
        .size:           4
        .value_kind:     hidden_dynamic_lds_size
    .group_segment_fixed_size: 0
    .kernarg_segment_align: 8
    .kernarg_segment_size: 528
    .language:       OpenCL C
    .language_version:
      - 2
      - 0
    .max_flat_workgroup_size: 512
    .name:           _Z10fwd_kernel4Args
    .private_segment_fixed_size: 0
    .sgpr_count:     104
    .sgpr_spill_count: 126
    .symbol:         _Z10fwd_kernel4Args.kd
    .uniform_work_group_size: 1
    .uses_dynamic_stack: false
    .vgpr_count:     256
    .vgpr_spill_count: 0
    .wavefront_size: 64
